# align_nsa_loop_pad64
# baseline (speedup 1.0000x reference)
.LBB0_421:
	s_add_i32 s0, 0, 0x22ff0
	v_writelane_b32 v254, s0, 7
	s_waitcnt vmcnt(2)
	v_mov_b32_e32 v91, s0
	s_add_i32 s0, 0, 0x19c00
	v_writelane_b32 v254, s0, 8
	s_add_i32 s0, 0, 0x1bc00
	v_writelane_b32 v254, s0, 9
	v_writelane_b32 v254, s86, 10
	v_cmp_eq_u32_e64 s[8:9], 0, v113
	s_add_i32 s65, 0, 0x11c00
	v_writelane_b32 v254, s87, 11
	v_writelane_b32 v254, s88, 12
	s_mov_b32 s43, 0
	v_mov_b32_e32 v77, 0
	v_writelane_b32 v254, s89, 13
	v_writelane_b32 v254, s90, 14
	s_movk_i32 s10, 0x90
	s_waitcnt vmcnt(1)
	v_mov_b32_e32 v92, 0xf149f2ca
	v_writelane_b32 v254, s91, 15
	v_writelane_b32 v254, s92, 16
	v_mbcnt_hi_u32_b32 v174, -1, v230
	v_mov_b32_e32 v93, 0x80
	v_writelane_b32 v254, s93, 17
	v_writelane_b32 v254, s85, 18
	v_writelane_b32 v254, s94, 19
	v_mov_b32_e32 v94, 0x100
	v_mov_b32_e32 v95, 0x200
	v_writelane_b32 v254, s95, 20
	v_writelane_b32 v254, s71, 21
	v_writelane_b32 v254, s72, 22
	v_writelane_b32 v254, s74, 23
	s_waitcnt vmcnt(0)
	v_mov_b32_e32 v96, 0x400
	v_mov_b32_e32 v97, 0x800
	v_writelane_b32 v254, s75, 24
	v_writelane_b32 v254, s96, 25
	v_writelane_b32 v254, s97, 26
	v_writelane_b32 v254, s66, 27
	v_mov_b32_e32 v98, 0x1000
	v_mov_b32_e32 v99, 0x2000
	v_writelane_b32 v254, s67, 28
	v_writelane_b32 v254, s8, 29
	v_mov_b32_e32 v100, 0x4000
	v_mov_b32_e32 v101, 0x8000
	v_writelane_b32 v254, s9, 30
	v_mov_b32_e32 v102, 0xff800000
	v_writelane_b32 v254, s65, 31
	s_branch .LBB0_424
	s_nop 0
	s_nop 0
	s_nop 0
	s_nop 0
	s_nop 0
	s_nop 0
	s_nop 0
	s_nop 0
	s_nop 0
	s_nop 0
	s_nop 0
	s_nop 0
	s_nop 0
	s_nop 0
	s_nop 0
	s_nop 0
